# P0 weight-transpose loop software-pipelined: next tile loads issued before current tile LDS read/pack/store
# speedup vs baseline: 1.0156x; 1.0020x over previous
; #define LAS __attribute__((address_space(3)))
; __device__ __forceinline__ unsigned pk2(float lo, float hi) { return f2bf(lo) | (f2bf(hi) << 16); }
; __device__ __forceinline__ void p0_prologue(const Ctx& c0) {
;     ...
;           for (int q = 0; q < 16; ++q) { const int kk = q * 4 + (c.tid >> 7); v[q] = (sc >= 0) ? __builtin_nontemporal_load(W + (size_t)(k0 + kk) * Ns + sc) : 0.f; }
; #pragma unroll
;           for (int q = 0; q < 16; ++q) { const int kk = q * 4 + (c.tid >> 7); tile[kk * 129 + nn] = v[q]; } }
;         __syncthreads();
;         { const int n = c.tid >> 2, kc = (c.tid & 3) * 16; const LAS float* s = tile + kc * 129 + n;
;           u32x4 o0, o1;
;           o0.x = pk2(s[0], s[129]); o0.y = pk2(s[2 * 129], s[3 * 129]); o0.z = pk2(s[4 * 129], s[5 * 129]); o0.w = pk2(s[6 * 129], s[7 * 129]);
;           o1.x = pk2(s[8 * 129], s[9 * 129]); o1.y = pk2(s[10 * 129], s[11 * 129]); o1.z = pk2(s[12 * 129], s[13 * 129]); o1.w = pk2(s[14 * 129], s[15 * 129]);
;           bf16* dp = WT + (size_t)(n0 + n) * K + k0 + kc; *(u32x4*)dp = o0; *(u32x4*)(dp + 8) = o1; }
;         __syncthreads();
.LBB0_12:
	s_or_b64 exec, exec, s[8:9]
	s_waitcnt vmcnt(0)
	ds_write_b32 v11, v12 offset:1024
	ds_write_b32 v11, v2 offset:3088
	ds_write_b32 v11, v14 offset:5152
	ds_write_b32 v11, v13 offset:7216
	ds_write_b32 v11, v16 offset:9280
	ds_write_b32 v11, v15 offset:11344
	ds_write_b32 v11, v18 offset:13408
	ds_write_b32 v11, v17 offset:15472
	ds_write_b32 v11, v20 offset:17536
	ds_write_b32 v11, v19 offset:19600
	ds_write_b32 v11, v22 offset:21664
	ds_write_b32 v11, v21 offset:23728
	ds_write_b32 v11, v24 offset:25792
	ds_write_b32 v11, v23 offset:27856
	ds_write_b32 v11, v26 offset:29920
	ds_write_b32 v11, v25 offset:31984
	s_ashr_i32 s11, s10, 31
	v_mov_b32_e32 v103, 0
	v_add_u32_e32 v102, s16, v9
	v_mad_u64_u32 v[106:107], s[6:7], v102, s24, 0
	v_ashrrev_i32_e32 v105, 31, v102
	v_mov_b32_e32 v102, v107
	v_mad_u64_u32 v[120:121], s[6:7], v105, s24, v[102:103]
	v_mov_b32_e32 v107, v120
	v_lshl_add_u64 v[106:107], v[106:107], 1, s[4:5]
	v_lshl_add_u64 v[106:107], s[10:11], 1, v[106:107]
	v_mov_b32_e32 v104, v4
	v_mov_b32_e32 v105, 0
	v_lshl_add_u64 v[124:125], v[106:107], 0, v[104:105]
	s_waitcnt lgkmcnt(0)
	s_barrier
	v_readlane_b32 s4, v253, 3
	s_add_i32 s23, s23, s4
	v_readlane_b32 s5, v253, 4
	s_cmpk_gt_i32 s23, 0xdff
	s_cbranch_scc1 .Lp0_Rlast

; #define LAS __attribute__((address_space(3)))
; __device__ __forceinline__ unsigned pk2(float lo, float hi) { return f2bf(lo) | (f2bf(hi) << 16); }
; __device__ __forceinline__ void p0_prologue(const Ctx& c0) {
;     ...
;           for (int q = 0; q < 16; ++q) { const int kk = q * 4 + (c.tid >> 7); tile[kk * 129 + nn] = v[q]; } }
;         __syncthreads();
;         { const int n = c.tid >> 2, kc = (c.tid & 3) * 16; const LAS float* s = tile + kc * 129 + n;
;           u32x4 o0, o1;
;           o0.x = pk2(s[0], s[129]); o0.y = pk2(s[2 * 129], s[3 * 129]); o0.z = pk2(s[4 * 129], s[5 * 129]); o0.w = pk2(s[6 * 129], s[7 * 129]);
;           o1.x = pk2(s[8 * 129], s[9 * 129]); o1.y = pk2(s[10 * 129], s[11 * 129]); o1.z = pk2(s[12 * 129], s[13 * 129]); o1.w = pk2(s[14 * 129], s[15 * 129]);
;           bf16* dp = WT + (size_t)(n0 + n) * K + k0 + kc; *(u32x4*)dp = o0; *(u32x4*)(dp + 8) = o1; }
;         __syncthreads();
;     }
.Lp0_R:
	s_or_b64 exec, exec, s[8:9]
	v_add_u32_e32 v102, 0x400, v10
	ds_read2_b32 v[106:107], v102 offset1:129
	v_add_u32_e32 v105, 0x800, v10
	ds_read2_b32 v[114:115], v105 offset0:2 offset1:131
	s_waitcnt lgkmcnt(1)
	v_bfe_u32 v102, v106, 16, 1
	v_add3_u32 v102, v106, v102, s21
	v_bfe_u32 v105, v107, 16, 1
	v_lshrrev_b32_e32 v102, 16, v102
	v_add3_u32 v105, v107, v105, s21
	v_and_or_b32 v112, v105, s22, v102
	s_waitcnt lgkmcnt(0)
	v_bfe_u32 v102, v114, 16, 1
	v_add_u32_e32 v105, 0xc00, v10
	v_add3_u32 v102, v114, v102, s21
	ds_read2_b32 v[106:107], v105 offset0:4 offset1:133
	v_bfe_u32 v105, v115, 16, 1
	v_lshrrev_b32_e32 v102, 16, v102
	v_add3_u32 v105, v115, v105, s21
	v_and_or_b32 v113, v105, s22, v102
	v_add_u32_e32 v105, 0x1000, v10
	ds_read2_b32 v[116:117], v105 offset0:6 offset1:135
	s_waitcnt lgkmcnt(1)
	v_bfe_u32 v102, v106, 16, 1
	v_add3_u32 v102, v106, v102, s21
	v_bfe_u32 v105, v107, 16, 1
	v_lshrrev_b32_e32 v102, 16, v102
	v_add3_u32 v105, v107, v105, s21
	v_and_or_b32 v114, v105, s22, v102
	s_waitcnt lgkmcnt(0)
	v_bfe_u32 v102, v116, 16, 1
	v_add_u32_e32 v105, 0x1400, v10
	v_add3_u32 v102, v116, v102, s21
	ds_read2_b32 v[106:107], v105 offset0:8 offset1:137
	v_bfe_u32 v105, v117, 16, 1
	v_lshrrev_b32_e32 v102, 16, v102
	v_add3_u32 v105, v117, v105, s21
	v_and_or_b32 v115, v105, s22, v102
	v_add_u32_e32 v105, 0x1800, v10
	ds_read2_b32 v[118:119], v105 offset0:10 offset1:139
	s_waitcnt lgkmcnt(1)
	v_bfe_u32 v102, v106, 16, 1
	v_add3_u32 v102, v106, v102, s21
	v_bfe_u32 v105, v107, 16, 1
	v_lshrrev_b32_e32 v102, 16, v102
	v_add3_u32 v105, v107, v105, s21
	v_and_or_b32 v116, v105, s22, v102
	s_waitcnt lgkmcnt(0)
	v_bfe_u32 v102, v118, 16, 1
	v_add_u32_e32 v105, 0x1c00, v10
	v_add3_u32 v102, v118, v102, s21
	ds_read2_b32 v[106:107], v105 offset0:12 offset1:141
	v_bfe_u32 v105, v119, 16, 1
	v_lshrrev_b32_e32 v102, 16, v102
	v_add3_u32 v105, v119, v105, s21
	v_and_or_b32 v117, v105, s22, v102
	v_add_u32_e32 v105, 0x2000, v10
	ds_read2_b32 v[120:121], v105 offset0:14 offset1:143
	s_waitcnt lgkmcnt(1)
	v_bfe_u32 v102, v106, 16, 1
	v_add3_u32 v102, v106, v102, s21
	v_bfe_u32 v105, v107, 16, 1
	v_lshrrev_b32_e32 v102, 16, v102
	v_add3_u32 v105, v107, v105, s21
	v_and_or_b32 v118, v105, s22, v102
	s_waitcnt lgkmcnt(0)
	v_bfe_u32 v102, v120, 16, 1
	v_add3_u32 v102, v120, v102, s21
	v_bfe_u32 v105, v121, 16, 1
	v_lshrrev_b32_e32 v102, 16, v102
	v_add3_u32 v105, v121, v105, s21
	v_and_or_b32 v119, v105, s22, v102
	global_store_dwordx4 v[124:125], v[112:115], off
	global_store_dwordx4 v[124:125], v[116:119], off offset:16
	s_barrier
	s_branch .LBB0_12
.Lp0_Rlast:
	v_add_u32_e32 v102, 0x400, v10
	ds_read2_b32 v[106:107], v102 offset1:129
	v_add_u32_e32 v105, 0x800, v10
	ds_read2_b32 v[114:115], v105 offset0:2 offset1:131
	s_waitcnt lgkmcnt(1)
	v_bfe_u32 v102, v106, 16, 1
	v_add3_u32 v102, v106, v102, s21
	v_bfe_u32 v105, v107, 16, 1
	v_lshrrev_b32_e32 v102, 16, v102
	v_add3_u32 v105, v107, v105, s21
	v_and_or_b32 v112, v105, s22, v102
	s_waitcnt lgkmcnt(0)
	v_bfe_u32 v102, v114, 16, 1
	v_add_u32_e32 v105, 0xc00, v10
	v_add3_u32 v102, v114, v102, s21
	ds_read2_b32 v[106:107], v105 offset0:4 offset1:133
	v_bfe_u32 v105, v115, 16, 1
	v_lshrrev_b32_e32 v102, 16, v102
	v_add3_u32 v105, v115, v105, s21
	v_and_or_b32 v113, v105, s22, v102
	v_add_u32_e32 v105, 0x1000, v10
	ds_read2_b32 v[116:117], v105 offset0:6 offset1:135
	s_waitcnt lgkmcnt(1)
	v_bfe_u32 v102, v106, 16, 1
	v_add3_u32 v102, v106, v102, s21
	v_bfe_u32 v105, v107, 16, 1
	v_lshrrev_b32_e32 v102, 16, v102
	v_add3_u32 v105, v107, v105, s21
	v_and_or_b32 v114, v105, s22, v102
	s_waitcnt lgkmcnt(0)
	v_bfe_u32 v102, v116, 16, 1
	v_add_u32_e32 v105, 0x1400, v10
	v_add3_u32 v102, v116, v102, s21
	ds_read2_b32 v[106:107], v105 offset0:8 offset1:137
	v_bfe_u32 v105, v117, 16, 1
	v_lshrrev_b32_e32 v102, 16, v102
	v_add3_u32 v105, v117, v105, s21
	v_and_or_b32 v115, v105, s22, v102
	v_add_u32_e32 v105, 0x1800, v10
	ds_read2_b32 v[118:119], v105 offset0:10 offset1:139
	s_waitcnt lgkmcnt(1)
	v_bfe_u32 v102, v106, 16, 1
	v_add3_u32 v102, v106, v102, s21
	v_bfe_u32 v105, v107, 16, 1
	v_lshrrev_b32_e32 v102, 16, v102
	v_add3_u32 v105, v107, v105, s21
	v_and_or_b32 v116, v105, s22, v102
	s_waitcnt lgkmcnt(0)
	v_bfe_u32 v102, v118, 16, 1
	v_add_u32_e32 v105, 0x1c00, v10
	v_add3_u32 v102, v118, v102, s21
	ds_read2_b32 v[106:107], v105 offset0:12 offset1:141
	v_bfe_u32 v105, v119, 16, 1
	v_lshrrev_b32_e32 v102, 16, v102
	v_add3_u32 v105, v119, v105, s21
	v_and_or_b32 v117, v105, s22, v102
	v_add_u32_e32 v105, 0x2000, v10
	ds_read2_b32 v[120:121], v105 offset0:14 offset1:143
	s_waitcnt lgkmcnt(1)
	v_bfe_u32 v102, v106, 16, 1
	v_add3_u32 v102, v106, v102, s21
	v_bfe_u32 v105, v107, 16, 1
	v_lshrrev_b32_e32 v102, 16, v102
	v_add3_u32 v105, v107, v105, s21
	v_and_or_b32 v118, v105, s22, v102
	s_waitcnt lgkmcnt(0)
	v_bfe_u32 v102, v120, 16, 1
	v_add3_u32 v102, v120, v102, s21
	v_bfe_u32 v105, v121, 16, 1
	v_lshrrev_b32_e32 v102, 16, v102
	v_add3_u32 v105, v121, v105, s21
	v_and_or_b32 v119, v105, s22, v102
	global_store_dwordx4 v[124:125], v[112:115], off
	global_store_dwordx4 v[124:125], v[116:119], off offset:16
	s_barrier
	s_branch .LBB0_84
